# P6 nu scan rewritten: all 128 loads up front, decay factors computed once and shared via LDS, stores after the fmac chain
# baseline (speedup 1.0000x reference)
; DI void phase6_scan(const Params& p) {
;     ...
;     if (blockIdx.x >= gridDim.x - 4) {
;         const int e = (blockIdx.x - (gridDim.x - 4)) * 512 + tid;
;         const int bh = e >> 7, d = e & 127;
;         float* nb = (float*)(ws + OFF_NU) + (size_t)bh * 128 * 128 + d;
;         const float* bl = (const float*)(ws + OFF_BLAST) + bh * 128;
;         const float* ms = (const float*)(ws + OFF_MST) + bh * 132;
;         float n = 0.f;
;         for (int c0 = 0; c0 < 128; c0 += 16) {
;             float vv[16], dd[16];
; #pragma unroll
;             for (int i = 0; i < 16; ++i) { vv[i] = nb[(c0 + i) * 128]; dd[i] = __expf(bl[c0 + i] + ms[c0 + i] - ms[c0 + i + 1]); }
.LBB0_635:
	v_readlane_b32 s4, v254, 0
	v_readlane_b32 s5, v254, 1
	s_load_dword s0, s[4:5], 0x10
	s_load_dword s1, s[4:5], 0x0
	s_waitcnt lgkmcnt(0)
	s_lshr_b32 s0, s0, 16
	s_cmp_lg_u32 s0, 0
	s_cselect_b64 s[4:5], -1, 0
	s_cmp_lg_u64 s[4:5], 0
	s_addc_u32 s0, s1, 0
	s_cmp_lg_u64 s[4:5], 0
	s_addc_u32 s1, s1, -4
	s_cmp_ge_u32 s2, s1
	s_cbranch_scc0 .LBB0_638
	s_sub_i32 s0, s2, s0
	s_lshl_b32 s0, s0, 9
	s_addk_i32 s0, 0x800
	v_add_u32_e32 v4, s0, v109
	v_ashrrev_i32_e32 v2, 7, v4
	v_and_b32_e32 v8, 0x7f, v109
	v_lshlrev_b32_e32 v3, 9, v2
	v_mul_u32_u24_e32 v5, 0x210, v2
	v_lshlrev_b32_e32 v0, 16, v2
	s_add_u32 s34, s70, 0x33de000
	s_addc_u32 s35, s71, 0
	s_add_u32 s36, s70, 0x33e0000
	s_addc_u32 s37, s71, 0
	s_add_u32 s38, s70, 0x33e2100
	s_addc_u32 s39, s71, 0
	v_lshl_add_u32 v3, v8, 2, v3
	v_lshl_add_u32 v5, v8, 2, v5
	v_lshl_or_b32 v0, v8, 2, v0
	s_mov_b64 s[40:41], s[38:39]
	global_load_dword v10, v3, s[34:35]
	global_load_dword v11, v5, s[36:37]
	global_load_dword v12, v5, s[36:37] offset:4
	global_load_dword v110, v0, s[38:39]
	global_load_dword v111, v0, s[38:39] offset:512
	global_load_dword v112, v0, s[38:39] offset:1024
	global_load_dword v113, v0, s[38:39] offset:1536
	global_load_dword v114, v0, s[38:39] offset:2048
	global_load_dword v115, v0, s[38:39] offset:2560
	global_load_dword v116, v0, s[38:39] offset:3072
	global_load_dword v117, v0, s[38:39] offset:3584
	s_add_u32 s38, s38, 0x1000
	s_addc_u32 s39, s39, 0
	global_load_dword v118, v0, s[38:39]
	global_load_dword v119, v0, s[38:39] offset:512
	global_load_dword v120, v0, s[38:39] offset:1024
	global_load_dword v121, v0, s[38:39] offset:1536
	global_load_dword v122, v0, s[38:39] offset:2048
	global_load_dword v123, v0, s[38:39] offset:2560
	global_load_dword v124, v0, s[38:39] offset:3072
	global_load_dword v125, v0, s[38:39] offset:3584
	s_add_u32 s38, s38, 0x1000
	s_addc_u32 s39, s39, 0
	global_load_dword v126, v0, s[38:39]
	global_load_dword v127, v0, s[38:39] offset:512
	global_load_dword v140, v0, s[38:39] offset:1024
	global_load_dword v141, v0, s[38:39] offset:1536
	global_load_dword v142, v0, s[38:39] offset:2048
	global_load_dword v143, v0, s[38:39] offset:2560
	global_load_dword v144, v0, s[38:39] offset:3072
	global_load_dword v145, v0, s[38:39] offset:3584
	s_add_u32 s38, s38, 0x1000
	s_addc_u32 s39, s39, 0
	global_load_dword v146, v0, s[38:39]
	global_load_dword v147, v0, s[38:39] offset:512
	global_load_dword v148, v0, s[38:39] offset:1024
	global_load_dword v149, v0, s[38:39] offset:1536
	global_load_dword v150, v0, s[38:39] offset:2048
	global_load_dword v151, v0, s[38:39] offset:2560
	global_load_dword v152, v0, s[38:39] offset:3072
	global_load_dword v153, v0, s[38:39] offset:3584
	s_add_u32 s38, s38, 0x1000
	s_addc_u32 s39, s39, 0
	global_load_dword v154, v0, s[38:39]
	global_load_dword v155, v0, s[38:39] offset:512
	global_load_dword v156, v0, s[38:39] offset:1024
	global_load_dword v157, v0, s[38:39] offset:1536
	global_load_dword v158, v0, s[38:39] offset:2048
	global_load_dword v159, v0, s[38:39] offset:2560
	global_load_dword v160, v0, s[38:39] offset:3072
	global_load_dword v161, v0, s[38:39] offset:3584
	s_add_u32 s38, s38, 0x1000
	s_addc_u32 s39, s39, 0
	global_load_dword v162, v0, s[38:39]
	global_load_dword v163, v0, s[38:39] offset:512
	global_load_dword v164, v0, s[38:39] offset:1024
	global_load_dword v165, v0, s[38:39] offset:1536
	global_load_dword v166, v0, s[38:39] offset:2048
	global_load_dword v167, v0, s[38:39] offset:2560
	global_load_dword v168, v0, s[38:39] offset:3072
	global_load_dword v169, v0, s[38:39] offset:3584
	s_add_u32 s38, s38, 0x1000
	s_addc_u32 s39, s39, 0
	global_load_dword v170, v0, s[38:39]
	global_load_dword v171, v0, s[38:39] offset:512
	global_load_dword v172, v0, s[38:39] offset:1024
	global_load_dword v173, v0, s[38:39] offset:1536
	global_load_dword v174, v0, s[38:39] offset:2048
	global_load_dword v175, v0, s[38:39] offset:2560
	global_load_dword v176, v0, s[38:39] offset:3072
	global_load_dword v177, v0, s[38:39] offset:3584
	s_add_u32 s38, s38, 0x1000
	s_addc_u32 s39, s39, 0
	global_load_dword v178, v0, s[38:39]
	global_load_dword v179, v0, s[38:39] offset:512
	global_load_dword v180, v0, s[38:39] offset:1024
	global_load_dword v181, v0, s[38:39] offset:1536
	s_waitcnt vmcnt(60)
; DI void phase6_scan(const Params& p) {
;     ...
;         for (int c0 = 0; c0 < 128; c0 += 16) {
;             float vv[16], dd[16];
; #pragma unroll
;             for (int i = 0; i < 16; ++i) { vv[i] = nb[(c0 + i) * 128]; dd[i] = __expf(bl[c0 + i] + ms[c0 + i] - ms[c0 + i + 1]); }
; #pragma unroll
;             for (int i = 0; i < 16; ++i) { nb[(c0 + i) * 128] = n; n = dd[i] * n + vv[i]; }
	v_add_f32_e32 v10, v10, v11
	v_sub_f32_e32 v10, v10, v12
	v_mul_f32_e32 v10, 0x3fb8aa3b, v10
	v_exp_f32_e32 v10, v10
	v_lshlrev_b32_e32 v13, 2, v109
	v_lshrrev_b32_e32 v14, 7, v109
	v_lshlrev_b32_e32 v14, 9, v14
	ds_write_b32 v13, v10 offset:1024
	global_load_dword v182, v0, s[38:39] offset:2048
	global_load_dword v183, v0, s[38:39] offset:2560
	global_load_dword v184, v0, s[38:39] offset:3072
	global_load_dword v185, v0, s[38:39] offset:3584
	s_add_u32 s38, s38, 0x1000
	s_addc_u32 s39, s39, 0
	global_load_dword v186, v0, s[38:39]
	global_load_dword v187, v0, s[38:39] offset:512
	global_load_dword v188, v0, s[38:39] offset:1024
	global_load_dword v189, v0, s[38:39] offset:1536
	global_load_dword v190, v0, s[38:39] offset:2048
	global_load_dword v191, v0, s[38:39] offset:2560
	global_load_dword v192, v0, s[38:39] offset:3072
	global_load_dword v193, v0, s[38:39] offset:3584
	s_add_u32 s38, s38, 0x1000
	s_addc_u32 s39, s39, 0
	global_load_dword v194, v0, s[38:39]
	global_load_dword v195, v0, s[38:39] offset:512
	global_load_dword v196, v0, s[38:39] offset:1024
	global_load_dword v197, v0, s[38:39] offset:1536
	global_load_dword v198, v0, s[38:39] offset:2048
	global_load_dword v199, v0, s[38:39] offset:2560
	global_load_dword v200, v0, s[38:39] offset:3072
	global_load_dword v201, v0, s[38:39] offset:3584
	s_add_u32 s38, s38, 0x1000
	s_addc_u32 s39, s39, 0
	global_load_dword v202, v0, s[38:39]
	global_load_dword v203, v0, s[38:39] offset:512
	global_load_dword v204, v0, s[38:39] offset:1024
	global_load_dword v205, v0, s[38:39] offset:1536
	global_load_dword v206, v0, s[38:39] offset:2048
	global_load_dword v207, v0, s[38:39] offset:2560
	global_load_dword v208, v0, s[38:39] offset:3072
	global_load_dword v209, v0, s[38:39] offset:3584
	s_add_u32 s38, s38, 0x1000
	s_addc_u32 s39, s39, 0
	global_load_dword v210, v0, s[38:39]
	global_load_dword v211, v0, s[38:39] offset:512
	global_load_dword v212, v0, s[38:39] offset:1024
	global_load_dword v213, v0, s[38:39] offset:1536
	global_load_dword v214, v0, s[38:39] offset:2048
	global_load_dword v215, v0, s[38:39] offset:2560
	global_load_dword v216, v0, s[38:39] offset:3072
	global_load_dword v217, v0, s[38:39] offset:3584
	s_add_u32 s38, s38, 0x1000
	s_addc_u32 s39, s39, 0
	global_load_dword v218, v0, s[38:39]
	global_load_dword v219, v0, s[38:39] offset:512
	global_load_dword v220, v0, s[38:39] offset:1024
	global_load_dword v221, v0, s[38:39] offset:1536
	global_load_dword v222, v0, s[38:39] offset:2048
	global_load_dword v223, v0, s[38:39] offset:2560
	global_load_dword v224, v0, s[38:39] offset:3072
	global_load_dword v225, v0, s[38:39] offset:3584
	s_add_u32 s38, s38, 0x1000
	s_addc_u32 s39, s39, 0
	global_load_dword v226, v0, s[38:39]
	global_load_dword v227, v0, s[38:39] offset:512
	global_load_dword v228, v0, s[38:39] offset:1024
	global_load_dword v229, v0, s[38:39] offset:1536
	global_load_dword v230, v0, s[38:39] offset:2048
	global_load_dword v231, v0, s[38:39] offset:2560
	global_load_dword v232, v0, s[38:39] offset:3072
	global_load_dword v233, v0, s[38:39] offset:3584
	s_add_u32 s38, s38, 0x1000
	s_addc_u32 s39, s39, 0
	global_load_dword v234, v0, s[38:39]
	global_load_dword v235, v0, s[38:39] offset:512
	global_load_dword v236, v0, s[38:39] offset:1024
	global_load_dword v237, v0, s[38:39] offset:1536
	global_load_dword v238, v0, s[38:39] offset:2048
	global_load_dword v239, v0, s[38:39] offset:2560
	global_load_dword v240, v0, s[38:39] offset:3072
	global_load_dword v241, v0, s[38:39] offset:3584
	s_add_u32 s38, s38, 0x1000
	s_addc_u32 s39, s39, 0
	global_load_dword v242, v0, s[38:39]
	global_load_dword v243, v0, s[38:39] offset:512
	global_load_dword v244, v0, s[38:39] offset:1024
	global_load_dword v245, v0, s[38:39] offset:1536
	global_load_dword v246, v0, s[38:39] offset:2048
	global_load_dword v247, v0, s[38:39] offset:2560
	global_load_dword v248, v0, s[38:39] offset:3072
	global_load_dword v249, v0, s[38:39] offset:3584
	v_mov_b32_e32 v6, 0
	s_waitcnt lgkmcnt(0)
	s_barrier
	ds_read_b128 v[16:19], v14 offset:1024
	ds_read_b128 v[20:23], v14 offset:1040
	ds_read_b128 v[24:27], v14 offset:1056
	ds_read_b128 v[28:31], v14 offset:1072
	ds_read_b128 v[32:35], v14 offset:1088
	ds_read_b128 v[36:39], v14 offset:1104
	ds_read_b128 v[40:43], v14 offset:1120
	ds_read_b128 v[44:47], v14 offset:1136
	s_waitcnt lgkmcnt(4)
	s_waitcnt vmcnt(63)
	v_fmac_f32_e32 v110, v6, v16
	v_fmac_f32_e32 v111, v110, v17
	v_fmac_f32_e32 v112, v111, v18
	v_fmac_f32_e32 v113, v112, v19
	v_fmac_f32_e32 v114, v113, v20
	v_fmac_f32_e32 v115, v114, v21
	v_fmac_f32_e32 v116, v115, v22
	v_fmac_f32_e32 v117, v116, v23
	v_fmac_f32_e32 v118, v117, v24
	v_fmac_f32_e32 v119, v118, v25
	v_fmac_f32_e32 v120, v119, v26
	v_fmac_f32_e32 v121, v120, v27
	v_fmac_f32_e32 v122, v121, v28
	v_fmac_f32_e32 v123, v122, v29
	v_fmac_f32_e32 v124, v123, v30
	v_fmac_f32_e32 v125, v124, v31
	ds_read_b128 v[16:19], v14 offset:1152
	ds_read_b128 v[20:23], v14 offset:1168
	ds_read_b128 v[24:27], v14 offset:1184
	ds_read_b128 v[28:31], v14 offset:1200
	s_waitcnt lgkmcnt(4)
	v_fmac_f32_e32 v126, v125, v32
	v_fmac_f32_e32 v127, v126, v33
	v_fmac_f32_e32 v140, v127, v34
	v_fmac_f32_e32 v141, v140, v35
	v_fmac_f32_e32 v142, v141, v36
	v_fmac_f32_e32 v143, v142, v37
	v_fmac_f32_e32 v144, v143, v38
	v_fmac_f32_e32 v145, v144, v39
	v_fmac_f32_e32 v146, v145, v40
	v_fmac_f32_e32 v147, v146, v41
	v_fmac_f32_e32 v148, v147, v42
	v_fmac_f32_e32 v149, v148, v43
	v_fmac_f32_e32 v150, v149, v44
	v_fmac_f32_e32 v151, v150, v45
	v_fmac_f32_e32 v152, v151, v46
	v_fmac_f32_e32 v153, v152, v47
	ds_read_b128 v[32:35], v14 offset:1216
	ds_read_b128 v[36:39], v14 offset:1232
	ds_read_b128 v[40:43], v14 offset:1248
	ds_read_b128 v[44:47], v14 offset:1264
	s_waitcnt lgkmcnt(4)
; DI void phase6_scan(const Params& p) {
;     ...
;             for (int i = 0; i < 16; ++i) { vv[i] = nb[(c0 + i) * 128]; dd[i] = __expf(bl[c0 + i] + ms[c0 + i] - ms[c0 + i + 1]); }
; #pragma unroll
;             for (int i = 0; i < 16; ++i) { nb[(c0 + i) * 128] = n; n = dd[i] * n + vv[i]; }
	v_fmac_f32_e32 v154, v153, v16
	v_fmac_f32_e32 v155, v154, v17
	v_fmac_f32_e32 v156, v155, v18
	v_fmac_f32_e32 v157, v156, v19
	v_fmac_f32_e32 v158, v157, v20
	v_fmac_f32_e32 v159, v158, v21
	v_fmac_f32_e32 v160, v159, v22
	v_fmac_f32_e32 v161, v160, v23
	v_fmac_f32_e32 v162, v161, v24
	v_fmac_f32_e32 v163, v162, v25
	v_fmac_f32_e32 v164, v163, v26
	v_fmac_f32_e32 v165, v164, v27
	v_fmac_f32_e32 v166, v165, v28
	v_fmac_f32_e32 v167, v166, v29
	v_fmac_f32_e32 v168, v167, v30
	v_fmac_f32_e32 v169, v168, v31
	ds_read_b128 v[16:19], v14 offset:1280
	ds_read_b128 v[20:23], v14 offset:1296
	ds_read_b128 v[24:27], v14 offset:1312
	ds_read_b128 v[28:31], v14 offset:1328
	s_waitcnt lgkmcnt(4)
	v_fmac_f32_e32 v170, v169, v32
	v_fmac_f32_e32 v171, v170, v33
	v_fmac_f32_e32 v172, v171, v34
	v_fmac_f32_e32 v173, v172, v35
	v_fmac_f32_e32 v174, v173, v36
	v_fmac_f32_e32 v175, v174, v37
	v_fmac_f32_e32 v176, v175, v38
	v_fmac_f32_e32 v177, v176, v39
	v_fmac_f32_e32 v178, v177, v40
	v_fmac_f32_e32 v179, v178, v41
	v_fmac_f32_e32 v180, v179, v42
	v_fmac_f32_e32 v181, v180, v43
	v_fmac_f32_e32 v182, v181, v44
	v_fmac_f32_e32 v183, v182, v45
	v_fmac_f32_e32 v184, v183, v46
	v_fmac_f32_e32 v185, v184, v47
	ds_read_b128 v[32:35], v14 offset:1344
	ds_read_b128 v[36:39], v14 offset:1360
	ds_read_b128 v[40:43], v14 offset:1376
	ds_read_b128 v[44:47], v14 offset:1392
	s_waitcnt lgkmcnt(4)
	v_fmac_f32_e32 v186, v185, v16
	s_waitcnt vmcnt(62)
	v_fmac_f32_e32 v187, v186, v17
	s_waitcnt vmcnt(61)
	v_fmac_f32_e32 v188, v187, v18
	s_waitcnt vmcnt(60)
	v_fmac_f32_e32 v189, v188, v19
	s_waitcnt vmcnt(59)
	v_fmac_f32_e32 v190, v189, v20
	s_waitcnt vmcnt(58)
	v_fmac_f32_e32 v191, v190, v21
	s_waitcnt vmcnt(57)
	v_fmac_f32_e32 v192, v191, v22
	s_waitcnt vmcnt(56)
	v_fmac_f32_e32 v193, v192, v23
	s_waitcnt vmcnt(55)
	v_fmac_f32_e32 v194, v193, v24
	s_waitcnt vmcnt(54)
	v_fmac_f32_e32 v195, v194, v25
	s_waitcnt vmcnt(53)
	v_fmac_f32_e32 v196, v195, v26
	s_waitcnt vmcnt(52)
	v_fmac_f32_e32 v197, v196, v27
	s_waitcnt vmcnt(51)
	v_fmac_f32_e32 v198, v197, v28
	s_waitcnt vmcnt(50)
	v_fmac_f32_e32 v199, v198, v29
	s_waitcnt vmcnt(49)
	v_fmac_f32_e32 v200, v199, v30
	s_waitcnt vmcnt(48)
	v_fmac_f32_e32 v201, v200, v31
	ds_read_b128 v[16:19], v14 offset:1408
	ds_read_b128 v[20:23], v14 offset:1424
	ds_read_b128 v[24:27], v14 offset:1440
	ds_read_b128 v[28:31], v14 offset:1456
	s_waitcnt lgkmcnt(4)
	s_waitcnt vmcnt(47)
	v_fmac_f32_e32 v202, v201, v32
	s_waitcnt vmcnt(46)
	v_fmac_f32_e32 v203, v202, v33
	s_waitcnt vmcnt(45)
	v_fmac_f32_e32 v204, v203, v34
	s_waitcnt vmcnt(44)
	v_fmac_f32_e32 v205, v204, v35
	s_waitcnt vmcnt(43)
	v_fmac_f32_e32 v206, v205, v36
	s_waitcnt vmcnt(42)
	v_fmac_f32_e32 v207, v206, v37
	s_waitcnt vmcnt(41)
	v_fmac_f32_e32 v208, v207, v38
	s_waitcnt vmcnt(40)
	v_fmac_f32_e32 v209, v208, v39
	s_waitcnt vmcnt(39)
	v_fmac_f32_e32 v210, v209, v40
	s_waitcnt vmcnt(38)
	v_fmac_f32_e32 v211, v210, v41
	s_waitcnt vmcnt(37)
	v_fmac_f32_e32 v212, v211, v42
	s_waitcnt vmcnt(36)
	v_fmac_f32_e32 v213, v212, v43
	s_waitcnt vmcnt(35)
	v_fmac_f32_e32 v214, v213, v44
	s_waitcnt vmcnt(34)
	v_fmac_f32_e32 v215, v214, v45
	s_waitcnt vmcnt(33)
	v_fmac_f32_e32 v216, v215, v46
	s_waitcnt vmcnt(32)
	v_fmac_f32_e32 v217, v216, v47
	ds_read_b128 v[32:35], v14 offset:1472
	ds_read_b128 v[36:39], v14 offset:1488
	ds_read_b128 v[40:43], v14 offset:1504
	ds_read_b128 v[44:47], v14 offset:1520
	s_waitcnt lgkmcnt(4)
	s_waitcnt vmcnt(31)
	v_fmac_f32_e32 v218, v217, v16
	s_waitcnt vmcnt(30)
	v_fmac_f32_e32 v219, v218, v17
	s_waitcnt vmcnt(29)
	v_fmac_f32_e32 v220, v219, v18
	s_waitcnt vmcnt(28)
	v_fmac_f32_e32 v221, v220, v19
	s_waitcnt vmcnt(27)
	v_fmac_f32_e32 v222, v221, v20
	s_waitcnt vmcnt(26)
	v_fmac_f32_e32 v223, v222, v21
	s_waitcnt vmcnt(25)
	v_fmac_f32_e32 v224, v223, v22
	s_waitcnt vmcnt(24)
	v_fmac_f32_e32 v225, v224, v23
	s_waitcnt vmcnt(23)
	v_fmac_f32_e32 v226, v225, v24
	s_waitcnt vmcnt(22)
	v_fmac_f32_e32 v227, v226, v25
	s_waitcnt vmcnt(21)
	v_fmac_f32_e32 v228, v227, v26
	s_waitcnt vmcnt(20)
	v_fmac_f32_e32 v229, v228, v27
	s_waitcnt vmcnt(19)
	v_fmac_f32_e32 v230, v229, v28
	s_waitcnt vmcnt(18)
	v_fmac_f32_e32 v231, v230, v29
	s_waitcnt vmcnt(17)
	v_fmac_f32_e32 v232, v231, v30
	s_waitcnt vmcnt(16)
	v_fmac_f32_e32 v233, v232, v31
	s_waitcnt lgkmcnt(0)
	s_waitcnt vmcnt(15)
	v_fmac_f32_e32 v234, v233, v32
	s_waitcnt vmcnt(14)
	v_fmac_f32_e32 v235, v234, v33
	s_waitcnt vmcnt(13)
	v_fmac_f32_e32 v236, v235, v34
	s_waitcnt vmcnt(12)
	v_fmac_f32_e32 v237, v236, v35
	s_waitcnt vmcnt(11)
	v_fmac_f32_e32 v238, v237, v36
	s_waitcnt vmcnt(10)
	v_fmac_f32_e32 v239, v238, v37
	s_waitcnt vmcnt(9)
	v_fmac_f32_e32 v240, v239, v38
	s_waitcnt vmcnt(8)
	v_fmac_f32_e32 v241, v240, v39
	s_waitcnt vmcnt(7)
	v_fmac_f32_e32 v242, v241, v40
	s_waitcnt vmcnt(6)
	v_fmac_f32_e32 v243, v242, v41
	s_waitcnt vmcnt(5)
	v_fmac_f32_e32 v244, v243, v42
	s_waitcnt vmcnt(4)
	v_fmac_f32_e32 v245, v244, v43
	s_waitcnt vmcnt(3)
	v_fmac_f32_e32 v246, v245, v44
	s_waitcnt vmcnt(2)
	v_fmac_f32_e32 v247, v246, v45
	s_waitcnt vmcnt(1)
	v_fmac_f32_e32 v248, v247, v46
	s_waitcnt vmcnt(0)
; DI void phase6_scan(const Params& p) {
;     ...
;             for (int i = 0; i < 16; ++i) { nb[(c0 + i) * 128] = n; n = dd[i] * n + vv[i]; }
;         }
	v_fmac_f32_e32 v249, v248, v47
	global_store_dword v0, v6, s[40:41]
	global_store_dword v0, v110, s[40:41] offset:512
	global_store_dword v0, v111, s[40:41] offset:1024
	global_store_dword v0, v112, s[40:41] offset:1536
	global_store_dword v0, v113, s[40:41] offset:2048
	global_store_dword v0, v114, s[40:41] offset:2560
	global_store_dword v0, v115, s[40:41] offset:3072
	global_store_dword v0, v116, s[40:41] offset:3584
	s_add_u32 s40, s40, 0x1000
	s_addc_u32 s41, s41, 0
	global_store_dword v0, v117, s[40:41]
	global_store_dword v0, v118, s[40:41] offset:512
	global_store_dword v0, v119, s[40:41] offset:1024
	global_store_dword v0, v120, s[40:41] offset:1536
	global_store_dword v0, v121, s[40:41] offset:2048
	global_store_dword v0, v122, s[40:41] offset:2560
	global_store_dword v0, v123, s[40:41] offset:3072
	global_store_dword v0, v124, s[40:41] offset:3584
	s_add_u32 s40, s40, 0x1000
	s_addc_u32 s41, s41, 0
	global_store_dword v0, v125, s[40:41]
	global_store_dword v0, v126, s[40:41] offset:512
	global_store_dword v0, v127, s[40:41] offset:1024
	global_store_dword v0, v140, s[40:41] offset:1536
	global_store_dword v0, v141, s[40:41] offset:2048
	global_store_dword v0, v142, s[40:41] offset:2560
	global_store_dword v0, v143, s[40:41] offset:3072
	global_store_dword v0, v144, s[40:41] offset:3584
	s_add_u32 s40, s40, 0x1000
	s_addc_u32 s41, s41, 0
	global_store_dword v0, v145, s[40:41]
	global_store_dword v0, v146, s[40:41] offset:512
	global_store_dword v0, v147, s[40:41] offset:1024
	global_store_dword v0, v148, s[40:41] offset:1536
	global_store_dword v0, v149, s[40:41] offset:2048
	global_store_dword v0, v150, s[40:41] offset:2560
	global_store_dword v0, v151, s[40:41] offset:3072
	global_store_dword v0, v152, s[40:41] offset:3584
	s_add_u32 s40, s40, 0x1000
	s_addc_u32 s41, s41, 0
	global_store_dword v0, v153, s[40:41]
	global_store_dword v0, v154, s[40:41] offset:512
	global_store_dword v0, v155, s[40:41] offset:1024
	global_store_dword v0, v156, s[40:41] offset:1536
	global_store_dword v0, v157, s[40:41] offset:2048
	global_store_dword v0, v158, s[40:41] offset:2560
	global_store_dword v0, v159, s[40:41] offset:3072
	global_store_dword v0, v160, s[40:41] offset:3584
	s_add_u32 s40, s40, 0x1000
	s_addc_u32 s41, s41, 0
	global_store_dword v0, v161, s[40:41]
	global_store_dword v0, v162, s[40:41] offset:512
	global_store_dword v0, v163, s[40:41] offset:1024
	global_store_dword v0, v164, s[40:41] offset:1536
	global_store_dword v0, v165, s[40:41] offset:2048
	global_store_dword v0, v166, s[40:41] offset:2560
	global_store_dword v0, v167, s[40:41] offset:3072
	global_store_dword v0, v168, s[40:41] offset:3584
	s_add_u32 s40, s40, 0x1000
	s_addc_u32 s41, s41, 0
	global_store_dword v0, v169, s[40:41]
	global_store_dword v0, v170, s[40:41] offset:512
	global_store_dword v0, v171, s[40:41] offset:1024
	global_store_dword v0, v172, s[40:41] offset:1536
	global_store_dword v0, v173, s[40:41] offset:2048
	global_store_dword v0, v174, s[40:41] offset:2560
	global_store_dword v0, v175, s[40:41] offset:3072
	global_store_dword v0, v176, s[40:41] offset:3584
	s_add_u32 s40, s40, 0x1000
	s_addc_u32 s41, s41, 0
	global_store_dword v0, v177, s[40:41]
	global_store_dword v0, v178, s[40:41] offset:512
	global_store_dword v0, v179, s[40:41] offset:1024
	global_store_dword v0, v180, s[40:41] offset:1536
	global_store_dword v0, v181, s[40:41] offset:2048
	global_store_dword v0, v182, s[40:41] offset:2560
	global_store_dword v0, v183, s[40:41] offset:3072
	global_store_dword v0, v184, s[40:41] offset:3584
; DI void phase6_scan(const Params& p) {
;     ...
;             for (int i = 0; i < 16; ++i) { nb[(c0 + i) * 128] = n; n = dd[i] * n + vv[i]; }
;         }
	s_add_u32 s40, s40, 0x1000
	s_addc_u32 s41, s41, 0
	global_store_dword v0, v185, s[40:41]
	global_store_dword v0, v186, s[40:41] offset:512
	global_store_dword v0, v187, s[40:41] offset:1024
	global_store_dword v0, v188, s[40:41] offset:1536
	global_store_dword v0, v189, s[40:41] offset:2048
	global_store_dword v0, v190, s[40:41] offset:2560
	global_store_dword v0, v191, s[40:41] offset:3072
	global_store_dword v0, v192, s[40:41] offset:3584
	s_add_u32 s40, s40, 0x1000
	s_addc_u32 s41, s41, 0
	global_store_dword v0, v193, s[40:41]
	global_store_dword v0, v194, s[40:41] offset:512
	global_store_dword v0, v195, s[40:41] offset:1024
	global_store_dword v0, v196, s[40:41] offset:1536
	global_store_dword v0, v197, s[40:41] offset:2048
	global_store_dword v0, v198, s[40:41] offset:2560
	global_store_dword v0, v199, s[40:41] offset:3072
	global_store_dword v0, v200, s[40:41] offset:3584
	s_add_u32 s40, s40, 0x1000
	s_addc_u32 s41, s41, 0
	global_store_dword v0, v201, s[40:41]
	global_store_dword v0, v202, s[40:41] offset:512
	global_store_dword v0, v203, s[40:41] offset:1024
	global_store_dword v0, v204, s[40:41] offset:1536
	global_store_dword v0, v205, s[40:41] offset:2048
	global_store_dword v0, v206, s[40:41] offset:2560
	global_store_dword v0, v207, s[40:41] offset:3072
	global_store_dword v0, v208, s[40:41] offset:3584
	s_add_u32 s40, s40, 0x1000
	s_addc_u32 s41, s41, 0
	global_store_dword v0, v209, s[40:41]
	global_store_dword v0, v210, s[40:41] offset:512
	global_store_dword v0, v211, s[40:41] offset:1024
	global_store_dword v0, v212, s[40:41] offset:1536
	global_store_dword v0, v213, s[40:41] offset:2048
	global_store_dword v0, v214, s[40:41] offset:2560
	global_store_dword v0, v215, s[40:41] offset:3072
	global_store_dword v0, v216, s[40:41] offset:3584
	s_add_u32 s40, s40, 0x1000
	s_addc_u32 s41, s41, 0
	global_store_dword v0, v217, s[40:41]
	global_store_dword v0, v218, s[40:41] offset:512
	global_store_dword v0, v219, s[40:41] offset:1024
	global_store_dword v0, v220, s[40:41] offset:1536
	global_store_dword v0, v221, s[40:41] offset:2048
	global_store_dword v0, v222, s[40:41] offset:2560
	global_store_dword v0, v223, s[40:41] offset:3072
	global_store_dword v0, v224, s[40:41] offset:3584
	s_add_u32 s40, s40, 0x1000
	s_addc_u32 s41, s41, 0
	global_store_dword v0, v225, s[40:41]
	global_store_dword v0, v226, s[40:41] offset:512
	global_store_dword v0, v227, s[40:41] offset:1024
	global_store_dword v0, v228, s[40:41] offset:1536
	global_store_dword v0, v229, s[40:41] offset:2048
	global_store_dword v0, v230, s[40:41] offset:2560
	global_store_dword v0, v231, s[40:41] offset:3072
	global_store_dword v0, v232, s[40:41] offset:3584
	s_add_u32 s40, s40, 0x1000
	s_addc_u32 s41, s41, 0
	global_store_dword v0, v233, s[40:41]
	global_store_dword v0, v234, s[40:41] offset:512
	global_store_dword v0, v235, s[40:41] offset:1024
	global_store_dword v0, v236, s[40:41] offset:1536
	global_store_dword v0, v237, s[40:41] offset:2048
	global_store_dword v0, v238, s[40:41] offset:2560
	global_store_dword v0, v239, s[40:41] offset:3072
	global_store_dword v0, v240, s[40:41] offset:3584
	s_add_u32 s40, s40, 0x1000
	s_addc_u32 s41, s41, 0
	global_store_dword v0, v241, s[40:41]
	global_store_dword v0, v242, s[40:41] offset:512
	global_store_dword v0, v243, s[40:41] offset:1024
	global_store_dword v0, v244, s[40:41] offset:1536
	global_store_dword v0, v245, s[40:41] offset:2048
	global_store_dword v0, v246, s[40:41] offset:2560
	global_store_dword v0, v247, s[40:41] offset:3072
	global_store_dword v0, v248, s[40:41] offset:3584
